# v15 + prologue f32->bf16 row conversions software-pipelined (4 items per trip, next trip loads in flight)
# baseline (speedup 1.0000x reference)
; __device__ __forceinline__ void cvt_rows(const float* src, bf16_t* dst, size_t n8, size_t gtid, size_t gn) {
;     for (size_t i = gtid; i < n8; i += gn) { const f32x4 a = *(const GASP f32x4*)(src + 8 * i), b = *(const GASP f32x4*)(src + 8 * i + 4);
;         u32x4 o; o.x = pk2(a[0], a[1]); o.y = pk2(a[2], a[3]); o.z = pk2(b[0], b[1]); o.w = pk2(b[2], b[3]); *(GASP u32x4*)(dst + 8 * i) = o; }
; }
; __device__ __forceinline__ void phase_prep(const Params& p, LAS unsigned char* lds) {
;     unsigned char* ws = p.ws; const int G = gridDim.x, bx = blockIdx.x;
;     if (bx == 0 && threadIdx.x < 64) ((unsigned*)(ws + O_CTR))[threadIdx.x] = 0u;
;     LAS float* tile = (LAS float*)lds;
;     constexpr int I_GU = 16 * 88, I_DN = 44 * 16, I_IN = 16 * 40, I_SQ = 16 * 16;
;     constexpr int NIT = 2 * I_GU + 2 * I_DN + I_IN + 5 * I_SQ;
;     for (int it = bx; it < NIT; it += G) {
;         int r = it;
;         if (r < I_GU) { transpose_item(p.in[7], D, 2 * FF, (bf16_t*)(ws + O_WGU1), r, 1, tile); continue; } r -= I_GU;
;         if (r < I_GU) { transpose_item(p.in[30], D, 2 * FF, (bf16_t*)(ws + O_WGU2), r, 1, tile, p.in[28], p.in[29], (float*)(ws + O_C1P) + C_GU2, (float*)(ws + O_C2P) + C_GU2); continue; } r -= I_GU;
;         if (r < I_DN) { transpose_item(p.in[8], FF, D, (bf16_t*)(ws + O_WDN1), r, 0, tile); continue; } r -= I_DN;
;         if (r < I_DN) { transpose_item(p.in[31], FF, D, (bf16_t*)(ws + O_WDN2), r, 0, tile); continue; } r -= I_DN;
;         if (r < I_IN) { transpose_item(p.in[11], D, INC, (bf16_t*)(ws + O_WIN), r, 0, tile, p.in[9], p.in[10], (float*)(ws + O_C1P) + C_IN, (float*)(ws + O_C2P) + C_IN); continue; } r -= I_IN;
;         if (r < I_SQ) { transpose_item(p.in[21], D, D, (bf16_t*)(ws + O_WOUT), r, 0, tile); continue; } r -= I_SQ;
;         if (r < I_SQ) { transpose_item(p.in[24], D, D, (bf16_t*)(ws + O_WQ), r, 0, tile, p.in[22], p.in[23], (float*)(ws + O_C1P) + C_Q, (float*)(ws + O_C2P) + C_Q); continue; } r -= I_SQ;
;         if (r < I_SQ) { transpose_item(p.in[25], D, D, (bf16_t*)(ws + O_WKV), r, 0, tile); continue; } r -= I_SQ;
;         if (r < I_SQ) { transpose_item(p.in[26], D, D, (bf16_t*)(ws + O_WKV) + (size_t)D * D, r, 0, tile); continue; } r -= I_SQ;
;         transpose_item(p.in[27], D, D, (bf16_t*)(ws + O_WO), r, 0, tile);
;     }
;     const size_t gtid = (size_t)bx * 512 + threadIdx.x, gn = (size_t)G * 512;
.LBB0_87:
	v_readlane_b32 s0, v252, 1
	v_readlane_b32 s1, v252, 2
	s_load_dwordx2 s[6:7], s[0:1], 0x98
	s_load_dwordx4 s[8:11], s[0:1], 0x0
	s_load_dwordx4 s[12:15], s[0:1], 0x20
	s_load_dwordx2 s[16:17], s[0:1], 0x30
	s_load_dwordx2 s[82:83], s[0:1], 0x128
	s_lshl_b64 s[0:1], s[2:3], 9
	v_lshl_add_u64 v[0:1], s[0:1], 0, v[208:209]
	s_lshl_b64 s[18:19], s[58:59], 9
	s_lshl_b32 s20, s2, 14
	s_lshl_b32 s21, s2, 13
	v_lshlrev_b32_e32 v2, 5, v208
	v_lshlrev_b32_e32 v3, 4, v208
	v_add_u32_e32 v2, s20, v2
	v_add_u32_e32 v3, s21, v3
	s_waitcnt lgkmcnt(0)
	s_mov_b32 s22, s8
	s_mov_b32 s23, s9
	global_load_dwordx4 v[10:13], v2, s[22:23]
	global_load_dwordx4 v[14:17], v2, s[22:23] offset:16
	s_add_u32 s22, s8, 0x400000
	s_addc_u32 s23, s9, 0
	global_load_dwordx4 v[18:21], v2, s[22:23]
	global_load_dwordx4 v[22:25], v2, s[22:23] offset:16
	s_add_u32 s22, s8, 0x800000
	s_addc_u32 s23, s9, 0
	global_load_dwordx4 v[26:29], v2, s[22:23]
	global_load_dwordx4 v[30:33], v2, s[22:23] offset:16
	s_add_u32 s22, s8, 0xc00000
	s_addc_u32 s23, s9, 0
	global_load_dwordx4 v[34:37], v2, s[22:23]
	global_load_dwordx4 v[38:41], v2, s[22:23] offset:16
	s_add_u32 s22, s8, 0x1000000
	s_addc_u32 s23, s9, 0
	global_load_dwordx4 v[42:45], v2, s[22:23]
	global_load_dwordx4 v[46:49], v2, s[22:23] offset:16
	s_add_u32 s22, s8, 0x1400000
	s_addc_u32 s23, s9, 0
	global_load_dwordx4 v[50:53], v2, s[22:23]
	global_load_dwordx4 v[54:57], v2, s[22:23] offset:16
	s_add_u32 s22, s8, 0x1800000
	s_addc_u32 s23, s9, 0
	global_load_dwordx4 v[58:61], v2, s[22:23]
	global_load_dwordx4 v[62:65], v2, s[22:23] offset:16
	s_add_u32 s22, s8, 0x1c00000
	s_addc_u32 s23, s9, 0
	global_load_dwordx4 v[66:69], v2, s[22:23]
	global_load_dwordx4 v[70:73], v2, s[22:23] offset:16
	s_waitcnt vmcnt(8)
	v_cvt_pk_bf16_f32 v10, v10, v11
	v_cvt_pk_bf16_f32 v11, v12, v13
	v_cvt_pk_bf16_f32 v12, v14, v15
	v_cvt_pk_bf16_f32 v13, v16, v17
	v_cvt_pk_bf16_f32 v18, v18, v19
	v_cvt_pk_bf16_f32 v19, v20, v21
	v_cvt_pk_bf16_f32 v20, v22, v23
	v_cvt_pk_bf16_f32 v21, v24, v25
	v_cvt_pk_bf16_f32 v26, v26, v27
	v_cvt_pk_bf16_f32 v27, v28, v29
	v_cvt_pk_bf16_f32 v28, v30, v31
	v_cvt_pk_bf16_f32 v29, v32, v33
	v_cvt_pk_bf16_f32 v34, v34, v35
	v_cvt_pk_bf16_f32 v35, v36, v37
	v_cvt_pk_bf16_f32 v36, v38, v39
	v_cvt_pk_bf16_f32 v37, v40, v41
	s_add_u32 s24, s52, 0x3021000
	s_addc_u32 s25, s53, 0
	global_store_dwordx4 v3, v[10:13], s[24:25]
	s_add_u32 s24, s52, 0x3221000
	s_addc_u32 s25, s53, 0
	global_store_dwordx4 v3, v[18:21], s[24:25]
	s_add_u32 s24, s52, 0x3421000
	s_addc_u32 s25, s53, 0
	global_store_dwordx4 v3, v[26:29], s[24:25]
	s_add_u32 s24, s52, 0x3621000
	s_addc_u32 s25, s53, 0
	global_store_dwordx4 v3, v[34:37], s[24:25]
	s_add_u32 s22, s8, 0x2000000
	s_addc_u32 s23, s9, 0
	global_load_dwordx4 v[10:13], v2, s[22:23]
	global_load_dwordx4 v[14:17], v2, s[22:23] offset:16
	s_add_u32 s22, s8, 0x2400000
	s_addc_u32 s23, s9, 0
	global_load_dwordx4 v[18:21], v2, s[22:23]
	global_load_dwordx4 v[22:25], v2, s[22:23] offset:16
	s_add_u32 s22, s8, 0x2800000
	s_addc_u32 s23, s9, 0
	global_load_dwordx4 v[26:29], v2, s[22:23]
	global_load_dwordx4 v[30:33], v2, s[22:23] offset:16
	s_add_u32 s22, s8, 0x2c00000
	s_addc_u32 s23, s9, 0
	global_load_dwordx4 v[34:37], v2, s[22:23]
	global_load_dwordx4 v[38:41], v2, s[22:23] offset:16
	s_waitcnt vmcnt(12)
	v_cvt_pk_bf16_f32 v42, v42, v43
	v_cvt_pk_bf16_f32 v43, v44, v45
	v_cvt_pk_bf16_f32 v44, v46, v47
	v_cvt_pk_bf16_f32 v45, v48, v49
	v_cvt_pk_bf16_f32 v50, v50, v51
	v_cvt_pk_bf16_f32 v51, v52, v53
	v_cvt_pk_bf16_f32 v52, v54, v55
	v_cvt_pk_bf16_f32 v53, v56, v57
	v_cvt_pk_bf16_f32 v58, v58, v59
	v_cvt_pk_bf16_f32 v59, v60, v61
	v_cvt_pk_bf16_f32 v60, v62, v63
	v_cvt_pk_bf16_f32 v61, v64, v65
	v_cvt_pk_bf16_f32 v66, v66, v67
	v_cvt_pk_bf16_f32 v67, v68, v69
	v_cvt_pk_bf16_f32 v68, v70, v71
	v_cvt_pk_bf16_f32 v69, v72, v73
	s_add_u32 s24, s52, 0x3821000
	s_addc_u32 s25, s53, 0
	global_store_dwordx4 v3, v[42:45], s[24:25]
	s_add_u32 s24, s52, 0x3a21000
	s_addc_u32 s25, s53, 0
	global_store_dwordx4 v3, v[50:53], s[24:25]
	s_add_u32 s24, s52, 0x3c21000
	s_addc_u32 s25, s53, 0
	global_store_dwordx4 v3, v[58:61], s[24:25]
	s_add_u32 s24, s52, 0x3e21000
	s_addc_u32 s25, s53, 0
	global_store_dwordx4 v3, v[66:69], s[24:25]
	s_add_u32 s22, s8, 0x3000000
	s_addc_u32 s23, s9, 0
	global_load_dwordx4 v[42:45], v2, s[22:23]
	global_load_dwordx4 v[46:49], v2, s[22:23] offset:16
	s_add_u32 s22, s8, 0x3400000
	s_addc_u32 s23, s9, 0
	global_load_dwordx4 v[50:53], v2, s[22:23]
	global_load_dwordx4 v[54:57], v2, s[22:23] offset:16
	s_add_u32 s22, s8, 0x3800000
	s_addc_u32 s23, s9, 0
	global_load_dwordx4 v[58:61], v2, s[22:23]
	global_load_dwordx4 v[62:65], v2, s[22:23] offset:16
	s_add_u32 s22, s8, 0x3c00000
	s_addc_u32 s23, s9, 0
	global_load_dwordx4 v[66:69], v2, s[22:23]
	global_load_dwordx4 v[70:73], v2, s[22:23] offset:16
	s_waitcnt vmcnt(12)
; __device__ __forceinline__ void cvt_rows(const float* src, bf16_t* dst, size_t n8, size_t gtid, size_t gn) {
;     for (size_t i = gtid; i < n8; i += gn) { const f32x4 a = *(const GASP f32x4*)(src + 8 * i), b = *(const GASP f32x4*)(src + 8 * i + 4);
;         u32x4 o; o.x = pk2(a[0], a[1]); o.y = pk2(a[2], a[3]); o.z = pk2(b[0], b[1]); o.w = pk2(b[2], b[3]); *(GASP u32x4*)(dst + 8 * i) = o; }
; }
; __device__ __forceinline__ void phase_prep(const Params& p, LAS unsigned char* lds) {
;     unsigned char* ws = p.ws; const int G = gridDim.x, bx = blockIdx.x;
;     if (bx == 0 && threadIdx.x < 64) ((unsigned*)(ws + O_CTR))[threadIdx.x] = 0u;
;     LAS float* tile = (LAS float*)lds;
;     constexpr int I_GU = 16 * 88, I_DN = 44 * 16, I_IN = 16 * 40, I_SQ = 16 * 16;
;     constexpr int NIT = 2 * I_GU + 2 * I_DN + I_IN + 5 * I_SQ;
;     for (int it = bx; it < NIT; it += G) {
;         int r = it;
;         if (r < I_GU) { transpose_item(p.in[7], D, 2 * FF, (bf16_t*)(ws + O_WGU1), r, 1, tile); continue; } r -= I_GU;
;         if (r < I_GU) { transpose_item(p.in[30], D, 2 * FF, (bf16_t*)(ws + O_WGU2), r, 1, tile, p.in[28], p.in[29], (float*)(ws + O_C1P) + C_GU2, (float*)(ws + O_C2P) + C_GU2); continue; } r -= I_GU;
;         if (r < I_DN) { transpose_item(p.in[8], FF, D, (bf16_t*)(ws + O_WDN1), r, 0, tile); continue; } r -= I_DN;
;         if (r < I_DN) { transpose_item(p.in[31], FF, D, (bf16_t*)(ws + O_WDN2), r, 0, tile); continue; } r -= I_DN;
;         if (r < I_IN) { transpose_item(p.in[11], D, INC, (bf16_t*)(ws + O_WIN), r, 0, tile, p.in[9], p.in[10], (float*)(ws + O_C1P) + C_IN, (float*)(ws + O_C2P) + C_IN); continue; } r -= I_IN;
;         if (r < I_SQ) { transpose_item(p.in[21], D, D, (bf16_t*)(ws + O_WOUT), r, 0, tile); continue; } r -= I_SQ;
;         if (r < I_SQ) { transpose_item(p.in[24], D, D, (bf16_t*)(ws + O_WQ), r, 0, tile, p.in[22], p.in[23], (float*)(ws + O_C1P) + C_Q, (float*)(ws + O_C2P) + C_Q); continue; } r -= I_SQ;
;         if (r < I_SQ) { transpose_item(p.in[25], D, D, (bf16_t*)(ws + O_WKV), r, 0, tile); continue; } r -= I_SQ;
;         if (r < I_SQ) { transpose_item(p.in[26], D, D, (bf16_t*)(ws + O_WKV) + (size_t)D * D, r, 0, tile); continue; } r -= I_SQ;
;         transpose_item(p.in[27], D, D, (bf16_t*)(ws + O_WO), r, 0, tile);
;     }
;     const size_t gtid = (size_t)bx * 512 + threadIdx.x, gn = (size_t)G * 512;
	v_cvt_pk_bf16_f32 v10, v10, v11
	v_cvt_pk_bf16_f32 v11, v12, v13
	v_cvt_pk_bf16_f32 v12, v14, v15
	v_cvt_pk_bf16_f32 v13, v16, v17
	v_cvt_pk_bf16_f32 v18, v18, v19
	v_cvt_pk_bf16_f32 v19, v20, v21
	v_cvt_pk_bf16_f32 v20, v22, v23
	v_cvt_pk_bf16_f32 v21, v24, v25
	v_cvt_pk_bf16_f32 v26, v26, v27
	v_cvt_pk_bf16_f32 v27, v28, v29
	v_cvt_pk_bf16_f32 v28, v30, v31
	v_cvt_pk_bf16_f32 v29, v32, v33
	v_cvt_pk_bf16_f32 v34, v34, v35
	v_cvt_pk_bf16_f32 v35, v36, v37
	v_cvt_pk_bf16_f32 v36, v38, v39
	v_cvt_pk_bf16_f32 v37, v40, v41
	s_add_u32 s24, s52, 0x4021000
	s_addc_u32 s25, s53, 0
	global_store_dwordx4 v3, v[10:13], s[24:25]
	s_add_u32 s24, s52, 0x4221000
	s_addc_u32 s25, s53, 0
	global_store_dwordx4 v3, v[18:21], s[24:25]
	s_add_u32 s24, s52, 0x4421000
	s_addc_u32 s25, s53, 0
	global_store_dwordx4 v3, v[26:29], s[24:25]
	s_add_u32 s24, s52, 0x4621000
	s_addc_u32 s25, s53, 0
	global_store_dwordx4 v3, v[34:37], s[24:25]
	s_add_u32 s22, s8, 0x4000000
	s_addc_u32 s23, s9, 0
	global_load_dwordx4 v[10:13], v2, s[22:23]
	global_load_dwordx4 v[14:17], v2, s[22:23] offset:16
	s_add_u32 s22, s8, 0x4400000
	s_addc_u32 s23, s9, 0
	global_load_dwordx4 v[18:21], v2, s[22:23]
	global_load_dwordx4 v[22:25], v2, s[22:23] offset:16
	s_add_u32 s22, s8, 0x4800000
	s_addc_u32 s23, s9, 0
	global_load_dwordx4 v[26:29], v2, s[22:23]
	global_load_dwordx4 v[30:33], v2, s[22:23] offset:16
	s_add_u32 s22, s8, 0x4c00000
	s_addc_u32 s23, s9, 0
	global_load_dwordx4 v[34:37], v2, s[22:23]
	global_load_dwordx4 v[38:41], v2, s[22:23] offset:16
	s_waitcnt vmcnt(12)
	v_cvt_pk_bf16_f32 v42, v42, v43
	v_cvt_pk_bf16_f32 v43, v44, v45
	v_cvt_pk_bf16_f32 v44, v46, v47
	v_cvt_pk_bf16_f32 v45, v48, v49
	v_cvt_pk_bf16_f32 v50, v50, v51
	v_cvt_pk_bf16_f32 v51, v52, v53
	v_cvt_pk_bf16_f32 v52, v54, v55
	v_cvt_pk_bf16_f32 v53, v56, v57
	v_cvt_pk_bf16_f32 v58, v58, v59
	v_cvt_pk_bf16_f32 v59, v60, v61
	v_cvt_pk_bf16_f32 v60, v62, v63
	v_cvt_pk_bf16_f32 v61, v64, v65
	v_cvt_pk_bf16_f32 v66, v66, v67
	v_cvt_pk_bf16_f32 v67, v68, v69
	v_cvt_pk_bf16_f32 v68, v70, v71
	v_cvt_pk_bf16_f32 v69, v72, v73
	s_add_u32 s24, s52, 0x4821000
	s_addc_u32 s25, s53, 0
	global_store_dwordx4 v3, v[42:45], s[24:25]
	s_add_u32 s24, s52, 0x4a21000
	s_addc_u32 s25, s53, 0
	global_store_dwordx4 v3, v[50:53], s[24:25]
	s_add_u32 s24, s52, 0x4c21000
	s_addc_u32 s25, s53, 0
	global_store_dwordx4 v3, v[58:61], s[24:25]
	s_add_u32 s24, s52, 0x4e21000
	s_addc_u32 s25, s53, 0
	global_store_dwordx4 v3, v[66:69], s[24:25]
	s_add_u32 s22, s8, 0x5000000
	s_addc_u32 s23, s9, 0
	global_load_dwordx4 v[42:45], v2, s[22:23]
	global_load_dwordx4 v[46:49], v2, s[22:23] offset:16
	s_add_u32 s22, s8, 0x5400000
	s_addc_u32 s23, s9, 0
	global_load_dwordx4 v[50:53], v2, s[22:23]
	global_load_dwordx4 v[54:57], v2, s[22:23] offset:16
	s_add_u32 s22, s8, 0x5800000
	s_addc_u32 s23, s9, 0
	global_load_dwordx4 v[58:61], v2, s[22:23]
	global_load_dwordx4 v[62:65], v2, s[22:23] offset:16
	s_add_u32 s22, s8, 0x5c00000
	s_addc_u32 s23, s9, 0
	global_load_dwordx4 v[66:69], v2, s[22:23]
	global_load_dwordx4 v[70:73], v2, s[22:23] offset:16
	s_waitcnt vmcnt(12)
	v_cvt_pk_bf16_f32 v10, v10, v11
	v_cvt_pk_bf16_f32 v11, v12, v13
	v_cvt_pk_bf16_f32 v12, v14, v15
	v_cvt_pk_bf16_f32 v13, v16, v17
	v_cvt_pk_bf16_f32 v18, v18, v19
	v_cvt_pk_bf16_f32 v19, v20, v21
	v_cvt_pk_bf16_f32 v20, v22, v23
	v_cvt_pk_bf16_f32 v21, v24, v25
	v_cvt_pk_bf16_f32 v26, v26, v27
	v_cvt_pk_bf16_f32 v27, v28, v29
	v_cvt_pk_bf16_f32 v28, v30, v31
	v_cvt_pk_bf16_f32 v29, v32, v33
	v_cvt_pk_bf16_f32 v34, v34, v35
	v_cvt_pk_bf16_f32 v35, v36, v37
	v_cvt_pk_bf16_f32 v36, v38, v39
	v_cvt_pk_bf16_f32 v37, v40, v41
	s_add_u32 s24, s52, 0x5021000
	s_addc_u32 s25, s53, 0
	global_store_dwordx4 v3, v[10:13], s[24:25]
	s_add_u32 s24, s52, 0x5221000
	s_addc_u32 s25, s53, 0
	global_store_dwordx4 v3, v[18:21], s[24:25]
	s_add_u32 s24, s52, 0x5421000
	s_addc_u32 s25, s53, 0
	global_store_dwordx4 v3, v[26:29], s[24:25]
	s_add_u32 s24, s52, 0x5621000
	s_addc_u32 s25, s53, 0
	global_store_dwordx4 v3, v[34:37], s[24:25]
	s_add_u32 s22, s8, 0x6000000
	s_addc_u32 s23, s9, 0
	global_load_dwordx4 v[10:13], v2, s[22:23]
	global_load_dwordx4 v[14:17], v2, s[22:23] offset:16
	s_add_u32 s22, s8, 0x6400000
	s_addc_u32 s23, s9, 0
	global_load_dwordx4 v[18:21], v2, s[22:23]
	global_load_dwordx4 v[22:25], v2, s[22:23] offset:16
	s_add_u32 s22, s8, 0x6800000
	s_addc_u32 s23, s9, 0
	global_load_dwordx4 v[26:29], v2, s[22:23]
	global_load_dwordx4 v[30:33], v2, s[22:23] offset:16
	s_add_u32 s22, s8, 0x6c00000
	s_addc_u32 s23, s9, 0
	global_load_dwordx4 v[34:37], v2, s[22:23]
	global_load_dwordx4 v[38:41], v2, s[22:23] offset:16
	s_waitcnt vmcnt(12)
	v_cvt_pk_bf16_f32 v42, v42, v43
	v_cvt_pk_bf16_f32 v43, v44, v45
	v_cvt_pk_bf16_f32 v44, v46, v47
	v_cvt_pk_bf16_f32 v45, v48, v49
	v_cvt_pk_bf16_f32 v50, v50, v51
	v_cvt_pk_bf16_f32 v51, v52, v53
	v_cvt_pk_bf16_f32 v52, v54, v55
	v_cvt_pk_bf16_f32 v53, v56, v57
	v_cvt_pk_bf16_f32 v58, v58, v59
	v_cvt_pk_bf16_f32 v59, v60, v61
	v_cvt_pk_bf16_f32 v60, v62, v63
	v_cvt_pk_bf16_f32 v61, v64, v65
	v_cvt_pk_bf16_f32 v66, v66, v67
	v_cvt_pk_bf16_f32 v67, v68, v69
	v_cvt_pk_bf16_f32 v68, v70, v71
	v_cvt_pk_bf16_f32 v69, v72, v73
	s_add_u32 s24, s52, 0x5821000
	s_addc_u32 s25, s53, 0
	global_store_dwordx4 v3, v[42:45], s[24:25]
	s_add_u32 s24, s52, 0x5a21000
	s_addc_u32 s25, s53, 0
	global_store_dwordx4 v3, v[50:53], s[24:25]
	s_add_u32 s24, s52, 0x5c21000
	s_addc_u32 s25, s53, 0
	global_store_dwordx4 v3, v[58:61], s[24:25]
	s_add_u32 s24, s52, 0x5e21000
	s_addc_u32 s25, s53, 0
	global_store_dwordx4 v3, v[66:69], s[24:25]
	s_add_u32 s22, s8, 0x7000000
	s_addc_u32 s23, s9, 0
	global_load_dwordx4 v[42:45], v2, s[22:23]
	global_load_dwordx4 v[46:49], v2, s[22:23] offset:16
	s_add_u32 s22, s8, 0x7400000
	s_addc_u32 s23, s9, 0
	global_load_dwordx4 v[50:53], v2, s[22:23]
	global_load_dwordx4 v[54:57], v2, s[22:23] offset:16
	s_add_u32 s22, s8, 0x7800000
	s_addc_u32 s23, s9, 0
	global_load_dwordx4 v[58:61], v2, s[22:23]
	global_load_dwordx4 v[62:65], v2, s[22:23] offset:16
	s_add_u32 s22, s8, 0x7c00000
	s_addc_u32 s23, s9, 0
	global_load_dwordx4 v[66:69], v2, s[22:23]
	global_load_dwordx4 v[70:73], v2, s[22:23] offset:16
	s_waitcnt vmcnt(12)
; __device__ __forceinline__ void cvt_rows(const float* src, bf16_t* dst, size_t n8, size_t gtid, size_t gn) {
;     for (size_t i = gtid; i < n8; i += gn) { const f32x4 a = *(const GASP f32x4*)(src + 8 * i), b = *(const GASP f32x4*)(src + 8 * i + 4);
;         u32x4 o; o.x = pk2(a[0], a[1]); o.y = pk2(a[2], a[3]); o.z = pk2(b[0], b[1]); o.w = pk2(b[2], b[3]); *(GASP u32x4*)(dst + 8 * i) = o; }
; }
; __device__ __forceinline__ void phase_prep(const Params& p, LAS unsigned char* lds) {
;     unsigned char* ws = p.ws; const int G = gridDim.x, bx = blockIdx.x;
;     if (bx == 0 && threadIdx.x < 64) ((unsigned*)(ws + O_CTR))[threadIdx.x] = 0u;
;     LAS float* tile = (LAS float*)lds;
;     constexpr int I_GU = 16 * 88, I_DN = 44 * 16, I_IN = 16 * 40, I_SQ = 16 * 16;
;     constexpr int NIT = 2 * I_GU + 2 * I_DN + I_IN + 5 * I_SQ;
;     for (int it = bx; it < NIT; it += G) {
;         int r = it;
;         if (r < I_GU) { transpose_item(p.in[7], D, 2 * FF, (bf16_t*)(ws + O_WGU1), r, 1, tile); continue; } r -= I_GU;
;         if (r < I_GU) { transpose_item(p.in[30], D, 2 * FF, (bf16_t*)(ws + O_WGU2), r, 1, tile, p.in[28], p.in[29], (float*)(ws + O_C1P) + C_GU2, (float*)(ws + O_C2P) + C_GU2); continue; } r -= I_GU;
;         if (r < I_DN) { transpose_item(p.in[8], FF, D, (bf16_t*)(ws + O_WDN1), r, 0, tile); continue; } r -= I_DN;
;         if (r < I_DN) { transpose_item(p.in[31], FF, D, (bf16_t*)(ws + O_WDN2), r, 0, tile); continue; } r -= I_DN;
;         if (r < I_IN) { transpose_item(p.in[11], D, INC, (bf16_t*)(ws + O_WIN), r, 0, tile, p.in[9], p.in[10], (float*)(ws + O_C1P) + C_IN, (float*)(ws + O_C2P) + C_IN); continue; } r -= I_IN;
;         if (r < I_SQ) { transpose_item(p.in[21], D, D, (bf16_t*)(ws + O_WOUT), r, 0, tile); continue; } r -= I_SQ;
;         if (r < I_SQ) { transpose_item(p.in[24], D, D, (bf16_t*)(ws + O_WQ), r, 0, tile, p.in[22], p.in[23], (float*)(ws + O_C1P) + C_Q, (float*)(ws + O_C2P) + C_Q); continue; } r -= I_SQ;
;         if (r < I_SQ) { transpose_item(p.in[25], D, D, (bf16_t*)(ws + O_WKV), r, 0, tile); continue; } r -= I_SQ;
;         if (r < I_SQ) { transpose_item(p.in[26], D, D, (bf16_t*)(ws + O_WKV) + (size_t)D * D, r, 0, tile); continue; } r -= I_SQ;
;         transpose_item(p.in[27], D, D, (bf16_t*)(ws + O_WO), r, 0, tile);
;     }
;     const size_t gtid = (size_t)bx * 512 + threadIdx.x, gn = (size_t)G * 512;
	v_cvt_pk_bf16_f32 v10, v10, v11
	v_cvt_pk_bf16_f32 v11, v12, v13
	v_cvt_pk_bf16_f32 v12, v14, v15
	v_cvt_pk_bf16_f32 v13, v16, v17
	v_cvt_pk_bf16_f32 v18, v18, v19
	v_cvt_pk_bf16_f32 v19, v20, v21
	v_cvt_pk_bf16_f32 v20, v22, v23
	v_cvt_pk_bf16_f32 v21, v24, v25
	v_cvt_pk_bf16_f32 v26, v26, v27
	v_cvt_pk_bf16_f32 v27, v28, v29
	v_cvt_pk_bf16_f32 v28, v30, v31
	v_cvt_pk_bf16_f32 v29, v32, v33
	v_cvt_pk_bf16_f32 v34, v34, v35
	v_cvt_pk_bf16_f32 v35, v36, v37
	v_cvt_pk_bf16_f32 v36, v38, v39
	v_cvt_pk_bf16_f32 v37, v40, v41
	s_add_u32 s24, s52, 0x6021000
	s_addc_u32 s25, s53, 0
	global_store_dwordx4 v3, v[10:13], s[24:25]
	s_add_u32 s24, s52, 0x6221000
	s_addc_u32 s25, s53, 0
	global_store_dwordx4 v3, v[18:21], s[24:25]
	s_add_u32 s24, s52, 0x6421000
	s_addc_u32 s25, s53, 0
	global_store_dwordx4 v3, v[26:29], s[24:25]
	s_add_u32 s24, s52, 0x6621000
	s_addc_u32 s25, s53, 0
	global_store_dwordx4 v3, v[34:37], s[24:25]
	s_mov_b32 s22, s10
	s_mov_b32 s23, s11
	global_load_dwordx4 v[10:13], v2, s[22:23]
	global_load_dwordx4 v[14:17], v2, s[22:23] offset:16
	s_mov_b32 s22, s16
	s_mov_b32 s23, s17
	global_load_dwordx4 v[18:21], v2, s[22:23]
	global_load_dwordx4 v[22:25], v2, s[22:23] offset:16
	s_add_u32 s22, s16, 0x400000
	s_addc_u32 s23, s17, 0
	global_load_dwordx4 v[26:29], v2, s[22:23]
	global_load_dwordx4 v[30:33], v2, s[22:23] offset:16
	s_add_u32 s22, s16, 0x800000
	s_addc_u32 s23, s17, 0
	global_load_dwordx4 v[34:37], v2, s[22:23]
	global_load_dwordx4 v[38:41], v2, s[22:23] offset:16
	s_waitcnt vmcnt(12)
	v_cvt_pk_bf16_f32 v42, v42, v43
	v_cvt_pk_bf16_f32 v43, v44, v45
	v_cvt_pk_bf16_f32 v44, v46, v47
	v_cvt_pk_bf16_f32 v45, v48, v49
	v_cvt_pk_bf16_f32 v50, v50, v51
	v_cvt_pk_bf16_f32 v51, v52, v53
	v_cvt_pk_bf16_f32 v52, v54, v55
	v_cvt_pk_bf16_f32 v53, v56, v57
	v_cvt_pk_bf16_f32 v58, v58, v59
	v_cvt_pk_bf16_f32 v59, v60, v61
	v_cvt_pk_bf16_f32 v60, v62, v63
	v_cvt_pk_bf16_f32 v61, v64, v65
	v_cvt_pk_bf16_f32 v66, v66, v67
	v_cvt_pk_bf16_f32 v67, v68, v69
	v_cvt_pk_bf16_f32 v68, v70, v71
	v_cvt_pk_bf16_f32 v69, v72, v73
	s_add_u32 s24, s52, 0x6821000
	s_addc_u32 s25, s53, 0
	global_store_dwordx4 v3, v[42:45], s[24:25]
	s_add_u32 s24, s52, 0x6a21000
	s_addc_u32 s25, s53, 0
	global_store_dwordx4 v3, v[50:53], s[24:25]
	s_add_u32 s24, s52, 0x6c21000
	s_addc_u32 s25, s53, 0
	global_store_dwordx4 v3, v[58:61], s[24:25]
	s_add_u32 s24, s52, 0x6e21000
	s_addc_u32 s25, s53, 0
	global_store_dwordx4 v3, v[66:69], s[24:25]
	s_add_u32 s22, s16, 0xc00000
	s_addc_u32 s23, s17, 0
	global_load_dwordx4 v[42:45], v2, s[22:23]
	global_load_dwordx4 v[46:49], v2, s[22:23] offset:16
	s_mov_b32 s22, s12
	s_mov_b32 s23, s13
	global_load_dwordx4 v[50:53], v2, s[22:23]
	global_load_dwordx4 v[54:57], v2, s[22:23] offset:16
	s_add_u32 s22, s12, 0x400000
	s_addc_u32 s23, s13, 0
	global_load_dwordx4 v[58:61], v2, s[22:23]
	global_load_dwordx4 v[62:65], v2, s[22:23] offset:16
	s_add_u32 s22, s12, 0x800000
	s_addc_u32 s23, s13, 0
	global_load_dwordx4 v[66:69], v2, s[22:23]
	global_load_dwordx4 v[70:73], v2, s[22:23] offset:16
	s_waitcnt vmcnt(12)
	v_cvt_pk_bf16_f32 v10, v10, v11
	v_cvt_pk_bf16_f32 v11, v12, v13
	v_cvt_pk_bf16_f32 v12, v14, v15
	v_cvt_pk_bf16_f32 v13, v16, v17
	v_cvt_pk_bf16_f32 v18, v18, v19
	v_cvt_pk_bf16_f32 v19, v20, v21
	v_cvt_pk_bf16_f32 v20, v22, v23
	v_cvt_pk_bf16_f32 v21, v24, v25
	v_cvt_pk_bf16_f32 v26, v26, v27
	v_cvt_pk_bf16_f32 v27, v28, v29
	v_cvt_pk_bf16_f32 v28, v30, v31
	v_cvt_pk_bf16_f32 v29, v32, v33
	v_cvt_pk_bf16_f32 v34, v34, v35
	v_cvt_pk_bf16_f32 v35, v36, v37
	v_cvt_pk_bf16_f32 v36, v38, v39
	v_cvt_pk_bf16_f32 v37, v40, v41
	s_add_u32 s24, s52, 0x7021000
	s_addc_u32 s25, s53, 0
	global_store_dwordx4 v3, v[10:13], s[24:25]
	s_add_u32 s24, s52, 0x1aba1000
	s_addc_u32 s25, s53, 0
	global_store_dwordx4 v3, v[18:21], s[24:25]
	s_add_u32 s24, s52, 0x1ada1000
	s_addc_u32 s25, s53, 0
	global_store_dwordx4 v3, v[26:29], s[24:25]
	s_add_u32 s24, s52, 0x1afa1000
	s_addc_u32 s25, s53, 0
	global_store_dwordx4 v3, v[34:37], s[24:25]
	s_add_u32 s22, s12, 0xc00000
	s_addc_u32 s23, s13, 0
	global_load_dwordx4 v[10:13], v2, s[22:23]
	global_load_dwordx4 v[14:17], v2, s[22:23] offset:16
	s_add_u32 s22, s12, 0x1000000
	s_addc_u32 s23, s13, 0
	global_load_dwordx4 v[18:21], v2, s[22:23]
	global_load_dwordx4 v[22:25], v2, s[22:23] offset:16
	s_add_u32 s22, s12, 0x1400000
	s_addc_u32 s23, s13, 0
	global_load_dwordx4 v[26:29], v2, s[22:23]
	global_load_dwordx4 v[30:33], v2, s[22:23] offset:16
	s_add_u32 s22, s12, 0x1800000
	s_addc_u32 s23, s13, 0
	global_load_dwordx4 v[34:37], v2, s[22:23]
	global_load_dwordx4 v[38:41], v2, s[22:23] offset:16
	s_waitcnt vmcnt(12)
; __device__ __forceinline__ void cvt_rows(const float* src, bf16_t* dst, size_t n8, size_t gtid, size_t gn) {
;     for (size_t i = gtid; i < n8; i += gn) { const f32x4 a = *(const GASP f32x4*)(src + 8 * i), b = *(const GASP f32x4*)(src + 8 * i + 4);
;         u32x4 o; o.x = pk2(a[0], a[1]); o.y = pk2(a[2], a[3]); o.z = pk2(b[0], b[1]); o.w = pk2(b[2], b[3]); *(GASP u32x4*)(dst + 8 * i) = o; }
; }
; __device__ __forceinline__ void phase_prep(const Params& p, LAS unsigned char* lds) {
;     unsigned char* ws = p.ws; const int G = gridDim.x, bx = blockIdx.x;
;     if (bx == 0 && threadIdx.x < 64) ((unsigned*)(ws + O_CTR))[threadIdx.x] = 0u;
;     LAS float* tile = (LAS float*)lds;
;     constexpr int I_GU = 16 * 88, I_DN = 44 * 16, I_IN = 16 * 40, I_SQ = 16 * 16;
;     constexpr int NIT = 2 * I_GU + 2 * I_DN + I_IN + 5 * I_SQ;
;     for (int it = bx; it < NIT; it += G) {
;         int r = it;
;         if (r < I_GU) { transpose_item(p.in[7], D, 2 * FF, (bf16_t*)(ws + O_WGU1), r, 1, tile); continue; } r -= I_GU;
;         if (r < I_GU) { transpose_item(p.in[30], D, 2 * FF, (bf16_t*)(ws + O_WGU2), r, 1, tile, p.in[28], p.in[29], (float*)(ws + O_C1P) + C_GU2, (float*)(ws + O_C2P) + C_GU2); continue; } r -= I_GU;
;         if (r < I_DN) { transpose_item(p.in[8], FF, D, (bf16_t*)(ws + O_WDN1), r, 0, tile); continue; } r -= I_DN;
;         if (r < I_DN) { transpose_item(p.in[31], FF, D, (bf16_t*)(ws + O_WDN2), r, 0, tile); continue; } r -= I_DN;
;         if (r < I_IN) { transpose_item(p.in[11], D, INC, (bf16_t*)(ws + O_WIN), r, 0, tile, p.in[9], p.in[10], (float*)(ws + O_C1P) + C_IN, (float*)(ws + O_C2P) + C_IN); continue; } r -= I_IN;
;         if (r < I_SQ) { transpose_item(p.in[21], D, D, (bf16_t*)(ws + O_WOUT), r, 0, tile); continue; } r -= I_SQ;
;         if (r < I_SQ) { transpose_item(p.in[24], D, D, (bf16_t*)(ws + O_WQ), r, 0, tile, p.in[22], p.in[23], (float*)(ws + O_C1P) + C_Q, (float*)(ws + O_C2P) + C_Q); continue; } r -= I_SQ;
;         if (r < I_SQ) { transpose_item(p.in[25], D, D, (bf16_t*)(ws + O_WKV), r, 0, tile); continue; } r -= I_SQ;
;         if (r < I_SQ) { transpose_item(p.in[26], D, D, (bf16_t*)(ws + O_WKV) + (size_t)D * D, r, 0, tile); continue; } r -= I_SQ;
;         transpose_item(p.in[27], D, D, (bf16_t*)(ws + O_WO), r, 0, tile);
;     }
;     const size_t gtid = (size_t)bx * 512 + threadIdx.x, gn = (size_t)G * 512;
	v_cvt_pk_bf16_f32 v42, v42, v43
	v_cvt_pk_bf16_f32 v43, v44, v45
	v_cvt_pk_bf16_f32 v44, v46, v47
	v_cvt_pk_bf16_f32 v45, v48, v49
	v_cvt_pk_bf16_f32 v50, v50, v51
	v_cvt_pk_bf16_f32 v51, v52, v53
	v_cvt_pk_bf16_f32 v52, v54, v55
	v_cvt_pk_bf16_f32 v53, v56, v57
	v_cvt_pk_bf16_f32 v58, v58, v59
	v_cvt_pk_bf16_f32 v59, v60, v61
	v_cvt_pk_bf16_f32 v60, v62, v63
	v_cvt_pk_bf16_f32 v61, v64, v65
	v_cvt_pk_bf16_f32 v66, v66, v67
	v_cvt_pk_bf16_f32 v67, v68, v69
	v_cvt_pk_bf16_f32 v68, v70, v71
	v_cvt_pk_bf16_f32 v69, v72, v73
	s_add_u32 s24, s52, 0x1b1a1000
	s_addc_u32 s25, s53, 0
	global_store_dwordx4 v3, v[42:45], s[24:25]
	s_add_u32 s24, s52, 0x1bba1000
	s_addc_u32 s25, s53, 0
	global_store_dwordx4 v3, v[50:53], s[24:25]
	s_add_u32 s24, s52, 0x1bda1000
	s_addc_u32 s25, s53, 0
	global_store_dwordx4 v3, v[58:61], s[24:25]
	s_add_u32 s24, s52, 0x1bfa1000
	s_addc_u32 s25, s53, 0
	global_store_dwordx4 v3, v[66:69], s[24:25]
	s_add_u32 s22, s12, 0x1c00000
	s_addc_u32 s23, s13, 0
	global_load_dwordx4 v[42:45], v2, s[22:23]
	global_load_dwordx4 v[46:49], v2, s[22:23] offset:16
	s_mov_b32 s22, s14
	s_mov_b32 s23, s15
	global_load_dwordx4 v[50:53], v2, s[22:23]
	global_load_dwordx4 v[54:57], v2, s[22:23] offset:16
	s_add_u32 s22, s14, 0x400000
	s_addc_u32 s23, s15, 0
	global_load_dwordx4 v[58:61], v2, s[22:23]
	global_load_dwordx4 v[62:65], v2, s[22:23] offset:16
	s_add_u32 s22, s14, 0x800000
	s_addc_u32 s23, s15, 0
	global_load_dwordx4 v[66:69], v2, s[22:23]
	global_load_dwordx4 v[70:73], v2, s[22:23] offset:16
	s_waitcnt vmcnt(12)
	v_cvt_pk_bf16_f32 v10, v10, v11
	v_cvt_pk_bf16_f32 v11, v12, v13
	v_cvt_pk_bf16_f32 v12, v14, v15
	v_cvt_pk_bf16_f32 v13, v16, v17
	v_cvt_pk_bf16_f32 v18, v18, v19
	v_cvt_pk_bf16_f32 v19, v20, v21
	v_cvt_pk_bf16_f32 v20, v22, v23
	v_cvt_pk_bf16_f32 v21, v24, v25
	v_cvt_pk_bf16_f32 v26, v26, v27
	v_cvt_pk_bf16_f32 v27, v28, v29
	v_cvt_pk_bf16_f32 v28, v30, v31
	v_cvt_pk_bf16_f32 v29, v32, v33
	v_cvt_pk_bf16_f32 v34, v34, v35
	v_cvt_pk_bf16_f32 v35, v36, v37
	v_cvt_pk_bf16_f32 v36, v38, v39
	v_cvt_pk_bf16_f32 v37, v40, v41
	s_add_u32 s24, s52, 0x1c1a1000
	s_addc_u32 s25, s53, 0
	global_store_dwordx4 v3, v[10:13], s[24:25]
	s_add_u32 s24, s52, 0x1c3a1000
	s_addc_u32 s25, s53, 0
	global_store_dwordx4 v3, v[18:21], s[24:25]
	s_add_u32 s24, s52, 0x1c5a1000
	s_addc_u32 s25, s53, 0
	global_store_dwordx4 v3, v[26:29], s[24:25]
	s_add_u32 s24, s52, 0x1c7a1000
	s_addc_u32 s25, s53, 0
	global_store_dwordx4 v3, v[34:37], s[24:25]
	s_add_u32 s22, s14, 0xc00000
	s_addc_u32 s23, s15, 0
	global_load_dwordx4 v[10:13], v2, s[22:23]
	global_load_dwordx4 v[14:17], v2, s[22:23] offset:16
	s_add_u32 s22, s14, 0x1000000
	s_addc_u32 s23, s15, 0
	global_load_dwordx4 v[18:21], v2, s[22:23]
	global_load_dwordx4 v[22:25], v2, s[22:23] offset:16
	s_add_u32 s22, s14, 0x1400000
	s_addc_u32 s23, s15, 0
	global_load_dwordx4 v[26:29], v2, s[22:23]
	global_load_dwordx4 v[30:33], v2, s[22:23] offset:16
	s_add_u32 s22, s14, 0x1800000
	s_addc_u32 s23, s15, 0
	global_load_dwordx4 v[34:37], v2, s[22:23]
	global_load_dwordx4 v[38:41], v2, s[22:23] offset:16
	s_waitcnt vmcnt(12)
	v_cvt_pk_bf16_f32 v42, v42, v43
	v_cvt_pk_bf16_f32 v43, v44, v45
	v_cvt_pk_bf16_f32 v44, v46, v47
	v_cvt_pk_bf16_f32 v45, v48, v49
	v_cvt_pk_bf16_f32 v50, v50, v51
	v_cvt_pk_bf16_f32 v51, v52, v53
	v_cvt_pk_bf16_f32 v52, v54, v55
	v_cvt_pk_bf16_f32 v53, v56, v57
	v_cvt_pk_bf16_f32 v58, v58, v59
	v_cvt_pk_bf16_f32 v59, v60, v61
	v_cvt_pk_bf16_f32 v60, v62, v63
	v_cvt_pk_bf16_f32 v61, v64, v65
	v_cvt_pk_bf16_f32 v66, v66, v67
	v_cvt_pk_bf16_f32 v67, v68, v69
	v_cvt_pk_bf16_f32 v68, v70, v71
	v_cvt_pk_bf16_f32 v69, v72, v73
	s_add_u32 s24, s52, 0x1c9a1000
	s_addc_u32 s25, s53, 0
	global_store_dwordx4 v3, v[42:45], s[24:25]
	s_add_u32 s24, s52, 0x1d3a1000
	s_addc_u32 s25, s53, 0
	global_store_dwordx4 v3, v[50:53], s[24:25]
	s_add_u32 s24, s52, 0x1d5a1000
	s_addc_u32 s25, s53, 0
	global_store_dwordx4 v3, v[58:61], s[24:25]
	s_add_u32 s24, s52, 0x1d7a1000
	s_addc_u32 s25, s53, 0
	global_store_dwordx4 v3, v[66:69], s[24:25]
	s_add_u32 s22, s14, 0x1c00000
	s_addc_u32 s23, s15, 0
	global_load_dwordx4 v[42:45], v2, s[22:23]
	global_load_dwordx4 v[46:49], v2, s[22:23] offset:16
	s_waitcnt vmcnt(6)
	v_cvt_pk_bf16_f32 v10, v10, v11
	v_cvt_pk_bf16_f32 v11, v12, v13
	v_cvt_pk_bf16_f32 v12, v14, v15
	v_cvt_pk_bf16_f32 v13, v16, v17
	v_cvt_pk_bf16_f32 v18, v18, v19
	v_cvt_pk_bf16_f32 v19, v20, v21
	v_cvt_pk_bf16_f32 v20, v22, v23
	v_cvt_pk_bf16_f32 v21, v24, v25
	v_cvt_pk_bf16_f32 v26, v26, v27
	v_cvt_pk_bf16_f32 v27, v28, v29
	v_cvt_pk_bf16_f32 v28, v30, v31
	v_cvt_pk_bf16_f32 v29, v32, v33
	v_cvt_pk_bf16_f32 v34, v34, v35
	v_cvt_pk_bf16_f32 v35, v36, v37
	v_cvt_pk_bf16_f32 v36, v38, v39
	v_cvt_pk_bf16_f32 v37, v40, v41
	s_add_u32 s24, s52, 0x1d9a1000
	s_addc_u32 s25, s53, 0
	global_store_dwordx4 v3, v[10:13], s[24:25]
	s_add_u32 s24, s52, 0x1dba1000
	s_addc_u32 s25, s53, 0
	global_store_dwordx4 v3, v[18:21], s[24:25]
	s_add_u32 s24, s52, 0x1dda1000
	s_addc_u32 s25, s53, 0
	global_store_dwordx4 v3, v[26:29], s[24:25]
	s_add_u32 s24, s52, 0x1dfa1000
	s_addc_u32 s25, s53, 0
	global_store_dwordx4 v3, v[34:37], s[24:25]
	s_waitcnt vmcnt(4)
	v_cvt_pk_bf16_f32 v42, v42, v43
	v_cvt_pk_bf16_f32 v43, v44, v45
	v_cvt_pk_bf16_f32 v44, v46, v47
	v_cvt_pk_bf16_f32 v45, v48, v49
	s_add_u32 s24, s52, 0x1e1a1000
	s_addc_u32 s25, s53, 0
	global_store_dwordx4 v3, v[42:45], s[24:25]
	s_mov_b64 s[0:1], 0x8000
	v_cmp_gt_u64_e32 vcc, s[0:1], v[0:1]
	s_and_saveexec_b64 s[8:9], vcc
	s_cbranch_execz .LBB0_108
	s_lshl_b64 s[0:1], s[2:3], 11
	s_add_u32 s0, s52, s0
	s_addc_u32 s1, s53, s1
	v_lshl_add_u64 v[2:3], v[208:209], 2, s[0:1]
	s_mov_b64 s[0:1], 0x3001000
	v_lshlrev_b32_e32 v4, 1, v208
	v_lshl_add_u64 v[2:3], v[2:3], 0, s[0:1]
	s_lshl_b64 s[10:11], s[58:59], 11
	v_lshl_add_u32 v4, s2, 10, v4
	s_waitcnt lgkmcnt(0)
	s_lshl_b32 s0, s82, 10
	s_mov_b64 s[12:13], 0
	v_mov_b32_e32 v5, 0
	s_mov_b64 s[14:15], 0x7fff
	s_branch .LBB0_104
